# v080 + P2 sgu head loop: 14 post-barrier global loads (WSb frags, PAU, bias) hoisted above the VT conversion into v176-v237 with recounted vmcnt waits
# speedup vs baseline: 1.0017x; 1.0017x over previous
.LBB0_396:
	v_lshl_add_u64 v[30:31], s[56:57], 0, v[28:29]
	v_lshl_add_u64 v[32:33], v[26:27], 0, s[8:9]
	v_lshl_add_u64 v[36:37], v[22:23], 0, s[8:9]
	ds_read_b128 v[4:7], v48 offset:4096
	ds_read_b128 v[0:3], v48 offset:4112
	v_lshl_add_u64 v[38:39], s[56:57], 0, v[24:25]
	v_lshl_add_u64 v[46:47], s[56:57], 0, v[20:21]
	v_lshl_add_u64 v[58:59], s[56:57], 0, v[16:17]
	global_load_dword v60, v[32:33], off
	s_nop 0
	global_load_dwordx4 v[30:33], v[30:31], off
	s_nop 0
	global_load_dwordx4 v[62:65], v[38:39], off
	global_load_dwordx4 v[66:69], v[46:47], off
	global_load_dwordx4 v[70:73], v[58:59], off
	s_nop 0
	global_load_dword v36, v[36:37], off
	v_lshl_add_u64 v[44:45], v[18:19], 0, s[8:9]
	v_lshl_add_u64 v[74:75], v[14:15], 0, s[8:9]
	global_load_dword v38, v[44:45], off
	s_nop 0
	global_load_dword v44, v[74:75], off
	s_bitcmp1_b32 s47, 0
	s_cselect_b32 s65, 0x8800, 0
	s_add_i32 s65, s65, 0
	v_add_u32_e32 v37, s65, v49
	v_add_u32_e32 v39, v37, v51
	v_add_u32_e32 v42, s64, v56
	v_ashrrev_i32_e32 v43, 31, v42
	v_lshl_add_u64 v[74:75], v[42:43], 1, s[38:39]
	v_add_u32_e32 v43, v37, v52
	v_add_u32_e32 v45, v37, v53
	v_add_u32_e32 v37, v37, v54
	v_add_u32_e32 v46, 0x800, v42
	v_ashrrev_i32_e32 v47, 31, v46
	v_lshl_add_u64 v[46:47], v[46:47], 1, s[38:39]
	v_add3_u32 v57, s65, v50, v55
	v_add_u32_e32 v58, 32, v42
	v_add_u32_e32 v94, 0x820, v42
	v_ashrrev_i32_e32 v59, 31, v58
	v_add_u32_e32 v100, 64, v42
	v_add_u32_e32 v102, 0x840, v42
	v_add_u32_e32 v104, 0x60, v42
	v_add_u32_e32 v106, 0x860, v42
	v_ashrrev_i32_e32 v95, 31, v94
	v_ashrrev_i32_e32 v101, 31, v100
	v_ashrrev_i32_e32 v103, 31, v102
	v_lshl_add_u64 v[98:99], s[56:57], 0, v[12:13]
	v_add_co_u32_e32 v110, vcc, s61, v98
	v_ashrrev_i32_e32 v105, 31, v104
	s_nop 0
	v_addc_co_u32_e32 v111, vcc, 0, v99, vcc
	v_lshl_add_u64 v[120:121], v[104:105], 1, s[38:39]
	v_ashrrev_i32_e32 v107, 31, v106
	v_lshl_add_u64 v[40:41], v[8:9], 0, s[8:9]
	v_lshl_add_u64 v[128:129], v[106:107], 1, s[38:39]
	v_lshl_add_u64 v[34:35], s[56:57], 0, v[10:11]
	v_add_co_u32_e32 v236, vcc, s61, v34
	global_load_dwordx4 v[176:179], v[74:75], off
	global_load_dwordx4 v[180:183], v[46:47], off
	v_addc_co_u32_e32 v237, vcc, 0, v35, vcc
	v_lshl_add_u64 v[228:229], v[58:59], 1, s[38:39]
	v_lshl_add_u64 v[230:231], v[94:95], 1, s[38:39]
	v_lshl_add_u64 v[232:233], v[100:101], 1, s[38:39]
	v_lshl_add_u64 v[234:235], v[102:103], 1, s[38:39]
	global_load_dwordx4 v[184:187], v[228:229], off
	global_load_dwordx4 v[188:191], v[230:231], off
	global_load_dwordx4 v[192:195], v[232:233], off
	global_load_dwordx4 v[196:199], v[234:235], off
	global_load_dwordx4 v[200:203], v[120:121], off
	global_load_dwordx4 v[204:207], v[128:129], off
	global_load_dwordx4 v[208:211], v[110:111], off
	global_load_dwordx4 v[212:215], v[110:111], off offset:64
	global_load_dword v224, v[40:41], off offset:-64
	global_load_dwordx4 v[216:219], v[236:237], off
	global_load_dwordx4 v[220:223], v[236:237], off offset:64
	global_load_dword v226, v[40:41], off
	s_add_i32 s47, s47, 1
	s_addk_i32 s64, 0x4000
	s_add_u32 s8, s8, 0x200
	s_addc_u32 s9, s9, 0
	v_lshl_add_u64 v[10:11], v[10:11], 0, s[44:45]
	v_lshl_add_u64 v[12:13], v[12:13], 0, s[44:45]
	v_lshl_add_u64 v[16:17], v[16:17], 0, s[40:41]
	v_lshl_add_u64 v[20:21], v[20:21], 0, s[40:41]
	v_lshl_add_u64 v[24:25], v[24:25], 0, s[40:41]
	v_lshl_add_u64 v[28:29], v[28:29], 0, s[40:41]
	s_cmp_lg_u32 s64, 0x10000
	s_waitcnt vmcnt(21) lgkmcnt(1)
	v_pk_mul_f32 v[6:7], v[6:7], v[60:61] op_sel_hi:[1,0]
	v_pk_mul_f32 v[4:5], v[4:5], v[60:61] op_sel_hi:[1,0]
	s_waitcnt lgkmcnt(0)
	v_pk_mul_f32 v[2:3], v[2:3], v[60:61] op_sel_hi:[1,0]
	v_pk_mul_f32 v[0:1], v[0:1], v[60:61] op_sel_hi:[1,0]
	s_waitcnt vmcnt(20)
	v_lshlrev_b32_e32 v76, 16, v30
	v_and_b32_e32 v77, 0xffff0000, v30
	v_lshlrev_b32_e32 v30, 16, v31
	v_and_b32_e32 v31, 0xffff0000, v31
	v_lshlrev_b32_e32 v78, 16, v32
	v_and_b32_e32 v79, 0xffff0000, v32
	v_lshlrev_b32_e32 v32, 16, v33
	v_and_b32_e32 v33, 0xffff0000, v33
	v_pk_mul_f32 v[4:5], v[4:5], v[76:77]
	v_pk_mul_f32 v[6:7], v[6:7], v[30:31]
	v_pk_mul_f32 v[30:31], v[0:1], v[78:79]
	v_pk_mul_f32 v[32:33], v[2:3], v[32:33]
	v_cvt_pk_bf16_f32 v0, v4, v5
	v_cvt_pk_bf16_f32 v1, v6, v7
	v_cvt_pk_bf16_f32 v2, v30, v31
	v_cvt_pk_bf16_f32 v3, v32, v33
	ds_write_b128 v39, v[0:3] offset:8192
	ds_read_b128 v[0:3], v48 offset:4096
	ds_read_b128 v[4:7], v48 offset:4112
	s_waitcnt vmcnt(19)
	v_lshlrev_b32_e32 v80, 16, v62
	v_and_b32_e32 v81, 0xffff0000, v62
	v_lshlrev_b32_e32 v62, 16, v63
	v_and_b32_e32 v63, 0xffff0000, v63
	v_lshlrev_b32_e32 v82, 16, v64
	v_and_b32_e32 v83, 0xffff0000, v64
	v_lshlrev_b32_e32 v64, 16, v65
	v_and_b32_e32 v65, 0xffff0000, v65
	s_waitcnt vmcnt(16) lgkmcnt(1)
	v_pk_mul_f32 v[2:3], v[2:3], v[36:37] op_sel_hi:[1,0]
	v_pk_mul_f32 v[0:1], v[0:1], v[36:37] op_sel_hi:[1,0]
	s_waitcnt lgkmcnt(0)
	v_pk_mul_f32 v[6:7], v[6:7], v[36:37] op_sel_hi:[1,0]
	v_pk_mul_f32 v[4:5], v[4:5], v[36:37] op_sel_hi:[1,0]
	v_pk_mul_f32 v[0:1], v[0:1], v[80:81]
	v_pk_mul_f32 v[2:3], v[2:3], v[62:63]
	v_pk_mul_f32 v[4:5], v[4:5], v[82:83]
	v_pk_mul_f32 v[6:7], v[6:7], v[64:65]
	v_cvt_pk_bf16_f32 v0, v0, v1
	v_cvt_pk_bf16_f32 v1, v2, v3
	v_cvt_pk_bf16_f32 v2, v4, v5
	v_cvt_pk_bf16_f32 v3, v6, v7
	ds_write_b128 v43, v[0:3] offset:8192
	ds_read_b128 v[0:3], v48 offset:4096
	ds_read_b128 v[4:7], v48 offset:4112
	v_lshlrev_b32_e32 v84, 16, v66
	v_and_b32_e32 v85, 0xffff0000, v66
	v_lshlrev_b32_e32 v66, 16, v67
	v_and_b32_e32 v67, 0xffff0000, v67
	v_lshlrev_b32_e32 v86, 16, v68
	v_and_b32_e32 v87, 0xffff0000, v68
	v_lshlrev_b32_e32 v68, 16, v69
	v_and_b32_e32 v69, 0xffff0000, v69
	s_waitcnt vmcnt(15) lgkmcnt(1)
	v_pk_mul_f32 v[2:3], v[2:3], v[38:39] op_sel_hi:[1,0]
	v_pk_mul_f32 v[0:1], v[0:1], v[38:39] op_sel_hi:[1,0]
	s_waitcnt lgkmcnt(0)
	v_pk_mul_f32 v[6:7], v[6:7], v[38:39] op_sel_hi:[1,0]
	v_pk_mul_f32 v[4:5], v[4:5], v[38:39] op_sel_hi:[1,0]
	v_pk_mul_f32 v[0:1], v[0:1], v[84:85]
	v_pk_mul_f32 v[2:3], v[2:3], v[66:67]
	v_pk_mul_f32 v[4:5], v[4:5], v[86:87]
	v_pk_mul_f32 v[6:7], v[6:7], v[68:69]
	v_cvt_pk_bf16_f32 v0, v0, v1
	v_cvt_pk_bf16_f32 v1, v2, v3
	v_cvt_pk_bf16_f32 v2, v4, v5
	v_cvt_pk_bf16_f32 v3, v6, v7
	ds_write_b128 v45, v[0:3] offset:8192
	ds_read_b128 v[0:3], v48 offset:4096
	ds_read_b128 v[4:7], v48 offset:4112
	v_lshlrev_b32_e32 v88, 16, v70
	v_and_b32_e32 v89, 0xffff0000, v70
	v_lshlrev_b32_e32 v70, 16, v71
	v_and_b32_e32 v71, 0xffff0000, v71
	v_lshlrev_b32_e32 v90, 16, v72
	v_and_b32_e32 v91, 0xffff0000, v72
	v_lshlrev_b32_e32 v72, 16, v73
	v_and_b32_e32 v73, 0xffff0000, v73
	s_waitcnt vmcnt(14) lgkmcnt(1)
	v_pk_mul_f32 v[2:3], v[2:3], v[44:45] op_sel_hi:[1,0]
	v_pk_mul_f32 v[0:1], v[0:1], v[44:45] op_sel_hi:[1,0]
	s_waitcnt lgkmcnt(0)
	v_pk_mul_f32 v[6:7], v[6:7], v[44:45] op_sel_hi:[1,0]
	v_pk_mul_f32 v[4:5], v[4:5], v[44:45] op_sel_hi:[1,0]
	v_pk_mul_f32 v[0:1], v[0:1], v[88:89]
	v_pk_mul_f32 v[2:3], v[2:3], v[70:71]
	v_pk_mul_f32 v[4:5], v[4:5], v[90:91]
	v_pk_mul_f32 v[6:7], v[6:7], v[72:73]
	v_cvt_pk_bf16_f32 v0, v0, v1
	v_cvt_pk_bf16_f32 v1, v2, v3
	v_cvt_pk_bf16_f32 v2, v4, v5
	v_cvt_pk_bf16_f32 v3, v6, v7
	ds_write_b128 v37, v[0:3] offset:8192
	s_waitcnt lgkmcnt(0)
	s_barrier
	ds_read_b128 v[30:33], v57 offset:8192
	ds_read_b128 v[36:39], v57 offset:8256
	ds_read_b128 v[62:65], v57 offset:12544
	ds_read_b128 v[66:69], v57 offset:12608
	ds_read_b128 v[74:77], v57 offset:16896
	ds_read_b128 v[78:81], v57 offset:16960
	ds_read_b128 v[86:89], v57 offset:21248
	ds_read_b128 v[90:93], v57 offset:21312
	v_lshl_add_u64 v[42:43], v[58:59], 1, s[38:39]
	v_lshl_add_u64 v[58:59], v[94:95], 1, s[38:39]
	s_waitcnt vmcnt(13) lgkmcnt(7)
	v_mfma_f32_16x16x32_bf16 v[44:47], v[30:33], v[176:179], 0
	s_waitcnt lgkmcnt(5)
	v_mfma_f32_16x16x32_bf16 v[70:73], v[62:65], v[176:179], 0
	s_waitcnt lgkmcnt(3)
	v_mfma_f32_16x16x32_bf16 v[82:85], v[74:77], v[176:179], 0
	s_waitcnt lgkmcnt(1)
	v_mfma_f32_16x16x32_bf16 v[0:3], v[86:89], v[176:179], 0
	s_waitcnt vmcnt(12)
	v_mfma_f32_16x16x32_bf16 v[30:33], v[30:33], v[180:183], 0
	v_mfma_f32_16x16x32_bf16 v[62:65], v[62:65], v[180:183], 0
	v_mfma_f32_16x16x32_bf16 v[74:77], v[74:77], v[180:183], 0
	v_mfma_f32_16x16x32_bf16 v[4:7], v[86:89], v[180:183], 0
	s_waitcnt vmcnt(11)
	v_mfma_f32_16x16x32_bf16 v[42:45], v[36:39], v[184:187], v[44:47]
	v_mfma_f32_16x16x32_bf16 v[70:73], v[66:69], v[184:187], v[70:73]
	s_nop 1
	v_add_co_u32_e32 v46, vcc, s62, v98
	v_mfma_f32_16x16x32_bf16 v[82:85], v[78:81], v[184:187], v[82:85]
	s_nop 0
	v_addc_co_u32_e32 v47, vcc, 0, v99, vcc
	v_add_co_u32_e32 v58, vcc, s61, v34
	s_waitcnt lgkmcnt(0)
	v_mfma_f32_16x16x32_bf16 v[0:3], v[90:93], v[184:187], v[0:3]
	v_lshl_add_u64 v[94:95], v[100:101], 1, s[38:39]
	v_lshl_add_u64 v[96:97], v[102:103], 1, s[38:39]
	v_addc_co_u32_e32 v59, vcc, 0, v35, vcc
	s_waitcnt vmcnt(10)
	v_mfma_f32_16x16x32_bf16 v[30:33], v[36:39], v[188:191], v[30:33]
	v_add_co_u32_e32 v34, vcc, s62, v34
	v_mfma_f32_16x16x32_bf16 v[36:39], v[66:69], v[188:191], v[62:65]
	s_nop 0
	v_addc_co_u32_e32 v35, vcc, 0, v35, vcc
	s_nop 0
	v_mfma_f32_16x16x32_bf16 v[66:69], v[78:81], v[188:191], v[74:77]
	s_nop 2
	v_mfma_f32_16x16x32_bf16 v[4:7], v[90:93], v[188:191], v[4:7]
	ds_read_b128 v[78:81], v57 offset:8320
	ds_read_b128 v[86:89], v57 offset:8384
	ds_read_b128 v[90:93], v57 offset:12672
	ds_read_b128 v[94:97], v57 offset:12736
	ds_read_b128 v[98:101], v57 offset:17024
	ds_read_b128 v[102:105], v57 offset:17088
	ds_read_b128 v[116:119], v57 offset:21376
	ds_read_b128 v[124:127], v57 offset:21440
	s_waitcnt vmcnt(9) lgkmcnt(7)
	v_mfma_f32_16x16x32_bf16 v[42:45], v[78:81], v[192:195], v[42:45]
	s_waitcnt lgkmcnt(5)
	v_mfma_f32_16x16x32_bf16 v[70:73], v[90:93], v[192:195], v[70:73]
	s_waitcnt lgkmcnt(3)
	v_mfma_f32_16x16x32_bf16 v[82:85], v[98:101], v[192:195], v[82:85]
	s_waitcnt lgkmcnt(1)
	v_mfma_f32_16x16x32_bf16 v[0:3], v[116:119], v[192:195], v[0:3]
	s_waitcnt vmcnt(5)
	v_lshlrev_b32_e32 v110, 16, v208
	v_mfma_f32_16x16x32_bf16 v[30:33], v[78:81], v[196:199], v[30:33]
	v_and_b32_e32 v111, 0xffff0000, v208
	s_waitcnt vmcnt(4)
	v_lshlrev_b32_e32 v106, 16, v214
	v_mfma_f32_16x16x32_bf16 v[42:45], v[86:89], v[200:203], v[42:45]
	v_mfma_f32_16x16x32_bf16 v[70:73], v[94:97], v[200:203], v[70:73]
	v_mfma_f32_16x16x32_bf16 v[82:85], v[102:105], v[200:203], v[82:85]
	s_waitcnt vmcnt(3)
	s_nop 4
	v_pk_add_f32 v[44:45], v[44:45], v[224:225] op_sel_hi:[1,0]
	s_waitcnt lgkmcnt(0)
	v_mfma_f32_16x16x32_bf16 v[0:3], v[124:127], v[200:203], v[0:3]
	v_add_f32_e64 v42, v42, v224
	v_add_f32_e64 v43, v43, v224
	v_pk_add_f32 v[72:73], v[72:73], v[224:225] op_sel_hi:[1,0]
	v_pk_add_f32 v[70:71], v[70:71], v[224:225] op_sel_hi:[1,0]
	v_mfma_f32_16x16x32_bf16 v[36:39], v[90:93], v[196:199], v[36:39]
	v_lshlrev_b32_e32 v90, 16, v209
	v_and_b32_e32 v91, 0xffff0000, v209
	v_lshlrev_b32_e32 v92, 16, v210
	v_mfma_f32_16x16x32_bf16 v[66:69], v[98:101], v[196:199], v[66:69]
	v_and_b32_e32 v93, 0xffff0000, v210
	v_lshlrev_b32_e32 v98, 16, v211
	v_and_b32_e32 v99, 0xffff0000, v211
	v_lshlrev_b32_e32 v100, 16, v212
	v_and_b32_e32 v101, 0xffff0000, v212
	v_lshlrev_b32_e32 v62, 16, v213
	v_and_b32_e32 v63, 0xffff0000, v213
	v_and_b32_e32 v107, 0xffff0000, v214
	v_lshlrev_b32_e32 v64, 16, v215
	v_and_b32_e32 v65, 0xffff0000, v215
	v_pk_add_f32 v[84:85], v[84:85], v[224:225] op_sel_hi:[1,0]
	v_pk_add_f32 v[82:83], v[82:83], v[224:225] op_sel_hi:[1,0]
	v_pk_add_f32 v[2:3], v[2:3], v[224:225] op_sel_hi:[1,0]
	v_pk_add_f32 v[0:1], v[0:1], v[224:225] op_sel_hi:[1,0]
	v_pk_mul_f32 v[42:43], v[42:43], v[110:111]
	v_pk_mul_f32 v[44:45], v[44:45], v[90:91]
	v_pk_mul_f32 v[70:71], v[70:71], v[92:93]
	v_pk_mul_f32 v[72:73], v[72:73], v[98:99]
	v_pk_mul_f32 v[82:83], v[82:83], v[100:101]
	v_pk_mul_f32 v[62:63], v[84:85], v[62:63]
	v_pk_mul_f32 v[84:85], v[0:1], v[106:107]
	v_pk_mul_f32 v[64:65], v[2:3], v[64:65]
	v_cvt_pk_bf16_f32 v0, v42, v43
	v_cvt_pk_bf16_f32 v1, v44, v45
	v_cvt_pk_bf16_f32 v2, v70, v71
	v_cvt_pk_bf16_f32 v3, v72, v73
	v_cvt_pk_bf16_f32 v42, v82, v83
	v_cvt_pk_bf16_f32 v43, v62, v63
	v_cvt_pk_bf16_f32 v44, v84, v85
	v_cvt_pk_bf16_f32 v45, v64, v65
	global_store_dwordx4 v[46:47], v[0:3], off
	global_store_dwordx4 v[46:47], v[42:45], off offset:64
	s_nop 0
	v_mfma_f32_16x16x32_bf16 v[4:7], v[116:119], v[196:199], v[4:7]
	s_waitcnt vmcnt(2)
	v_lshlrev_b32_e32 v58, 16, v216
	v_mfma_f32_16x16x32_bf16 v[30:33], v[86:89], v[204:207], v[30:33]
	v_and_b32_e32 v59, 0xffff0000, v216
	v_lshlrev_b32_e32 v0, 16, v217
	v_and_b32_e32 v1, 0xffff0000, v217
	v_mfma_f32_16x16x32_bf16 v[36:39], v[94:97], v[204:207], v[36:39]
	v_lshlrev_b32_e32 v62, 16, v218
	s_nop 2
	v_pk_add_f32 v[32:33], v[32:33], v[226:227] op_sel_hi:[1,0]
	v_pk_add_f32 v[30:31], v[30:31], v[226:227] op_sel_hi:[1,0]
	v_mfma_f32_16x16x32_bf16 v[44:47], v[102:105], v[204:207], v[66:69]
	v_and_b32_e32 v63, 0xffff0000, v218
	v_pk_add_f32 v[38:39], v[38:39], v[226:227] op_sel_hi:[1,0]
	v_pk_add_f32 v[36:37], v[36:37], v[226:227] op_sel_hi:[1,0]
	v_mfma_f32_16x16x32_bf16 v[4:7], v[124:127], v[204:207], v[4:7]
	v_lshlrev_b32_e32 v2, 16, v219
	v_and_b32_e32 v3, 0xffff0000, v219
	s_nop 1
	v_pk_add_f32 v[46:47], v[46:47], v[226:227] op_sel_hi:[1,0]
	v_pk_add_f32 v[44:45], v[44:45], v[226:227] op_sel_hi:[1,0]
	s_waitcnt vmcnt(2)
	v_lshlrev_b32_e32 v64, 16, v220
	v_pk_add_f32 v[6:7], v[6:7], v[226:227] op_sel_hi:[1,0]
	v_pk_add_f32 v[4:5], v[4:5], v[226:227] op_sel_hi:[1,0]
	v_and_b32_e32 v65, 0xffff0000, v220
	v_lshlrev_b32_e32 v40, 16, v221
	v_and_b32_e32 v41, 0xffff0000, v221
	v_lshlrev_b32_e32 v66, 16, v222
	v_and_b32_e32 v67, 0xffff0000, v222
	v_lshlrev_b32_e32 v42, 16, v223
	v_and_b32_e32 v43, 0xffff0000, v223
	v_pk_mul_f32 v[30:31], v[30:31], v[58:59]
	v_pk_mul_f32 v[32:33], v[32:33], v[0:1]
	v_pk_mul_f32 v[36:37], v[36:37], v[62:63]
	v_pk_mul_f32 v[38:39], v[38:39], v[2:3]
	v_pk_mul_f32 v[44:45], v[44:45], v[64:65]
	v_pk_mul_f32 v[40:41], v[46:47], v[40:41]
	v_pk_mul_f32 v[46:47], v[4:5], v[66:67]
	v_pk_mul_f32 v[42:43], v[6:7], v[42:43]
	v_cvt_pk_bf16_f32 v0, v30, v31
	v_cvt_pk_bf16_f32 v1, v32, v33
	v_cvt_pk_bf16_f32 v2, v36, v37
	v_cvt_pk_bf16_f32 v3, v38, v39
	v_cvt_pk_bf16_f32 v4, v44, v45
	v_cvt_pk_bf16_f32 v5, v40, v41
	v_cvt_pk_bf16_f32 v6, v46, v47
	v_cvt_pk_bf16_f32 v7, v42, v43
	global_store_dwordx4 v[34:35], v[0:3], off
	global_store_dwordx4 v[34:35], v[4:7], off offset:64
	s_cbranch_scc1 .LBB0_396
	v_mov_b32_e32 v0, v174
	s_barrier
	s_and_b32 s10, s10, 0xf80
	s_lshl_b32 s46, s46, 19
	v_ashrrev_i32_e32 v1, 2, v0
	s_add_u32 s8, s12, s46
	v_lshlrev_b32_e32 v0, 4, v0
	s_addc_u32 s9, s13, 0
	v_and_b32_e32 v60, 0x1f0, v0
	v_and_b32_e32 v66, -8, v1
	v_lshl_add_u64 v[64:65], s[8:9], 0, v[60:61]
	s_add_u32 s8, s66, s46
	s_addc_u32 s9, s67, 0
	v_or_b32_e32 v80, 1, v66
	v_or_b32_e32 v78, 2, v66
	v_or_b32_e32 v76, 3, v66
	v_or_b32_e32 v74, 4, v66
	v_or_b32_e32 v72, 5, v66
	v_or_b32_e32 v70, 6, v66
	v_or_b32_e32 v68, 7, v1
	v_lshl_add_u64 v[62:63], s[8:9], 0, v[60:61]
	s_mov_b64 s[8:9], -1
	s_cmp_lg_u32 s33, 0
	v_add_u32_e32 v124, -3, v66
	v_add_u32_e32 v123, -2, v66
	v_add_u32_e32 v125, -1, v66
	v_add_u32_e32 v122, s10, v66
	v_ashrrev_i32_e32 v67, 31, v66
	v_add_u32_e32 v121, s10, v80
	v_ashrrev_i32_e32 v81, 31, v80
	v_add_u32_e32 v120, s10, v78
	v_ashrrev_i32_e32 v79, 31, v78
	v_add_u32_e32 v119, s10, v76
	v_ashrrev_i32_e32 v77, 31, v76
	v_add_u32_e32 v118, s10, v74
	v_ashrrev_i32_e32 v75, 31, v74
	v_add_u32_e32 v117, s10, v72
	v_ashrrev_i32_e32 v73, 31, v72
	v_add_u32_e32 v116, s10, v70
	v_ashrrev_i32_e32 v71, 31, v70
	v_add_u32_e32 v60, s10, v68
	s_cbranch_scc0 .LBB0_399
	s_sub_i32 s8, 0, s10
	v_max_i32_e32 v0, s8, v124
	v_ashrrev_i32_e32 v1, 31, v0
	v_lshlrev_b64 v[0:1], 12, v[0:1]
	v_lshl_add_u64 v[22:23], v[64:65], 0, v[0:1]
	v_max_i32_e32 v0, s8, v123
	v_ashrrev_i32_e32 v1, 31, v0
	v_lshlrev_b64 v[0:1], 12, v[0:1]
	v_lshl_add_u64 v[28:29], v[64:65], 0, v[0:1]
	v_max_i32_e32 v0, s8, v125
	v_ashrrev_i32_e32 v1, 31, v0
	global_load_dwordx4 v[4:7], v[22:23], off offset:512
	v_lshlrev_b64 v[0:1], 12, v[0:1]
	global_load_dwordx4 v[8:11], v[28:29], off offset:512
	v_lshl_add_u64 v[30:31], v[64:65], 0, v[0:1]
	v_max_i32_e32 v0, s8, v66
	global_load_dwordx4 v[12:15], v[30:31], off offset:512
	v_ashrrev_i32_e32 v1, 31, v0
	v_lshlrev_b64 v[0:1], 12, v[0:1]
	v_lshl_add_u64 v[20:21], v[64:65], 0, v[0:1]
	global_load_dwordx4 v[0:3], v[20:21], off offset:512
	v_min_i32_e32 v17, 3, v122
	v_max_i32_e32 v16, s8, v80
	v_max_i32_e32 v18, s8, v78
	v_max_i32_e32 v24, s8, v76
	v_max_i32_e32 v26, s8, v74
	v_max_i32_e32 v32, s8, v72
	v_add_u32_e32 v35, 1, v17
	v_ashrrev_i32_e32 v17, 31, v16
	v_ashrrev_i32_e32 v19, 31, v18
	v_ashrrev_i32_e32 v25, 31, v24
	v_ashrrev_i32_e32 v27, 31, v26
	v_ashrrev_i32_e32 v33, 31, v32
	v_lshlrev_b64 v[16:17], 12, v[16:17]
	v_lshlrev_b64 v[18:19], 12, v[18:19]
	v_lshlrev_b64 v[24:25], 12, v[24:25]
	v_lshlrev_b64 v[26:27], 12, v[26:27]
	v_lshlrev_b64 v[40:41], 12, v[32:33]
	v_lshl_add_u64 v[32:33], v[64:65], 0, v[16:17]
	v_lshl_add_u64 v[84:85], v[64:65], 0, v[18:19]
	v_lshl_add_u64 v[58:59], v[64:65], 0, v[24:25]
	v_lshl_add_u64 v[56:57], v[64:65], 0, v[26:27]
	global_load_dwordx4 v[24:27], v[32:33], off offset:512
	global_load_dwordx4 v[16:19], v[84:85], off offset:512
	global_load_dwordx4 v[48:51], v[22:23], off offset:1024
	global_load_dwordx4 v[44:47], v[28:29], off offset:1024
	v_cvt_f32_i32_e32 v35, v35
	v_max_i32_e32 v36, s8, v70
	v_max_i32_e32 v38, s8, v68
	v_ashrrev_i32_e32 v37, 31, v36
	v_div_scale_f32 v22, s[46:47], v35, v35, 1.0
	v_rcp_f32_e32 v23, v22
	v_ashrrev_i32_e32 v39, 31, v38
	v_div_scale_f32 v28, vcc, 1.0, v35, 1.0
	v_fma_f32 v29, -v22, v23, 1.0
	v_fmac_f32_e32 v23, v29, v23
	v_lshlrev_b64 v[36:37], 12, v[36:37]
	v_lshlrev_b64 v[38:39], 12, v[38:39]
	v_mul_f32_e32 v29, v28, v23
	v_lshl_add_u64 v[54:55], v[64:65], 0, v[40:41]
	v_lshl_add_u64 v[52:53], v[64:65], 0, v[36:37]
	v_lshl_add_u64 v[82:83], v[64:65], 0, v[38:39]
	global_load_dwordx4 v[40:43], v[30:31], off offset:1024
	global_load_dwordx4 v[36:39], v[20:21], off offset:1024
	v_fma_f32 v30, -v22, v29, v28
	v_fmac_f32_e32 v29, v30, v23
	v_add_u32_e32 v34, s10, v124
	v_fma_f32 v22, -v22, v29, v28
	v_div_fmas_f32 v22, v22, v23, v29
	v_cmp_lt_i32_e32 vcc, -1, v34
	s_waitcnt vmcnt(6)
	v_lshlrev_b32_e32 v134, 16, v1
	v_cndmask_b32_e32 v23, 0, v7, vcc
	v_cndmask_b32_e32 v28, 0, v6, vcc
	v_cndmask_b32_e32 v5, 0, v5, vcc
	v_cndmask_b32_e32 v6, 0, v4, vcc
	v_cmp_lt_i32_e32 vcc, -2, v34
	v_lshlrev_b32_e32 v128, 16, v5
	v_and_b32_e32 v129, 0xffff0000, v5
	v_cndmask_b32_e32 v29, 0, v11, vcc
	v_cndmask_b32_e32 v10, 0, v10, vcc
	v_cndmask_b32_e32 v11, 0, v9, vcc
	v_cndmask_b32_e32 v8, 0, v8, vcc
	v_cmp_lt_i32_e32 vcc, -3, v34
	v_lshlrev_b32_e32 v106, 16, v8
	v_and_b32_e32 v107, 0xffff0000, v8
	v_cndmask_b32_e32 v9, 0, v12, vcc
	v_cndmask_b32_e32 v13, 0, v13, vcc
	v_lshlrev_b32_e32 v108, 16, v9
	v_and_b32_e32 v109, 0xffff0000, v9
	v_pk_add_f32 v[8:9], v[128:129], 0 op_sel_hi:[1,0]
	v_lshlrev_b32_e32 v130, 16, v11
	v_and_b32_e32 v131, 0xffff0000, v11
	v_pk_add_f32 v[8:9], v[8:9], v[130:131]
	v_lshlrev_b32_e32 v132, 16, v13
	v_and_b32_e32 v133, 0xffff0000, v13
	v_lshlrev_b32_e32 v86, 16, v6
	v_and_b32_e32 v87, 0xffff0000, v6
	v_pk_add_f32 v[8:9], v[8:9], v[132:133]
	v_and_b32_e32 v135, 0xffff0000, v1
	v_lshlrev_b32_e32 v138, 16, v28
	v_and_b32_e32 v139, 0xffff0000, v28
	v_lshlrev_b32_e32 v148, 16, v23
	v_and_b32_e32 v149, 0xffff0000, v23
	v_cndmask_b32_e32 v15, 0, v15, vcc
	v_cndmask_b32_e32 v14, 0, v14, vcc
	v_div_fixup_f32 v4, v22, v35, 1.0
	v_pk_add_f32 v[6:7], v[86:87], 0 op_sel_hi:[1,0]
	v_pk_add_f32 v[136:137], v[8:9], v[134:135]
	v_pk_add_f32 v[8:9], v[138:139], 0 op_sel_hi:[1,0]
	v_lshlrev_b32_e32 v140, 16, v10
	v_and_b32_e32 v141, 0xffff0000, v10
	v_pk_add_f32 v[10:11], v[148:149], 0 op_sel_hi:[1,0]
	v_lshlrev_b32_e32 v150, 16, v29
	v_and_b32_e32 v151, 0xffff0000, v29
	v_pk_add_f32 v[6:7], v[6:7], v[106:107]
	v_lshlrev_b32_e32 v110, 16, v0
	v_and_b32_e32 v111, 0xffff0000, v0
	v_pk_fma_f32 v[0:1], v[4:5], v[136:137], v[134:135] op_sel_hi:[0,1,1] neg_lo:[0,0,1] neg_hi:[0,0,1]
	v_pk_add_f32 v[8:9], v[8:9], v[140:141]
	v_lshlrev_b32_e32 v142, 16, v14
	v_and_b32_e32 v143, 0xffff0000, v14
	v_pk_add_f32 v[10:11], v[10:11], v[150:151]
	v_lshlrev_b32_e32 v152, 16, v15
	v_and_b32_e32 v153, 0xffff0000, v15
	v_pk_add_f32 v[6:7], v[6:7], v[108:109]
	v_pk_add_f32 v[8:9], v[8:9], v[142:143]
	v_lshlrev_b32_e32 v144, 16, v2
	v_and_b32_e32 v145, 0xffff0000, v2
	v_pk_add_f32 v[10:11], v[10:11], v[152:153]
	v_lshlrev_b32_e32 v154, 16, v3
	v_and_b32_e32 v155, 0xffff0000, v3
	v_cvt_pk_bf16_f32 v91, v0, v1
	v_min_i32_e32 v0, 3, v121
	v_pk_add_f32 v[126:127], v[6:7], v[110:111]
	v_pk_add_f32 v[146:147], v[8:9], v[144:145]
	v_pk_add_f32 v[156:157], v[10:11], v[154:155]
	v_add_u32_e32 v0, 1, v0
	v_pk_fma_f32 v[6:7], v[4:5], v[126:127], v[110:111] op_sel_hi:[0,1,1] neg_lo:[0,0,1] neg_hi:[0,0,1]
	v_pk_fma_f32 v[8:9], v[4:5], v[146:147], v[144:145] op_sel_hi:[0,1,1] neg_lo:[0,0,1] neg_hi:[0,0,1]
	v_pk_fma_f32 v[2:3], v[4:5], v[156:157], v[154:155] op_sel_hi:[0,1,1] neg_lo:[0,0,1] neg_hi:[0,0,1]
	v_cvt_f32_i32_e32 v69, v0
	v_lshlrev_b64 v[0:1], 12, v[66:67]
	v_cvt_pk_bf16_f32 v90, v6, v7
	v_cvt_pk_bf16_f32 v92, v8, v9
	v_cvt_pk_bf16_f32 v93, v2, v3
	v_lshl_add_u64 v[88:89], v[62:63], 0, v[0:1]
	global_load_dwordx4 v[32:35], v[32:33], off offset:1024
	s_nop 0
	global_load_dwordx4 v[28:31], v[84:85], off offset:1024
	global_load_dwordx4 v[94:97], v[58:59], off offset:512
	global_load_dwordx4 v[20:23], v[58:59], off offset:1024
	global_load_dwordx4 v[98:101], v[56:57], off offset:512
	global_load_dwordx4 v[12:15], v[56:57], off offset:1024
	global_load_dwordx4 v[102:105], v[54:55], off offset:512
	global_load_dwordx4 v[8:11], v[54:55], off offset:1024
	s_nop 0
	global_load_dwordx4 v[56:59], v[52:53], off offset:512
	global_load_dwordx4 v[4:7], v[52:53], off offset:1024
	s_nop 0
	global_load_dwordx4 v[52:55], v[82:83], off offset:512
	global_load_dwordx4 v[0:3], v[82:83], off offset:1024
	v_div_scale_f32 v158, s[46:47], v69, v69, 1.0
	v_rcp_f32_e32 v159, v158
	global_store_dwordx4 v[88:89], v[90:93], off offset:512
	v_fma_f32 v82, -v158, v159, 1.0
	v_fmac_f32_e32 v159, v82, v159
	v_div_scale_f32 v82, vcc, 1.0, v69, 1.0
	v_mul_f32_e32 v83, v82, v159
	v_fma_f32 v84, -v158, v83, v82
	v_fmac_f32_e32 v83, v84, v159
	v_fma_f32 v82, -v158, v83, v82
	v_pk_add_f32 v[92:93], v[136:137], v[128:129] neg_lo:[0,1] neg_hi:[0,1]
	s_waitcnt vmcnt(18)
	v_lshlrev_b32_e32 v136, 16, v26
	v_and_b32_e32 v137, 0xffff0000, v26
	v_min_i32_e32 v26, 3, v120
	v_div_fmas_f32 v82, v82, v159, v83
	v_add_u32_e32 v26, 1, v26
	v_div_fixup_f32 v82, v82, v69, 1.0
	v_cvt_f32_i32_e32 v69, v26
	v_pk_add_f32 v[84:85], v[126:127], v[86:87] neg_lo:[0,1] neg_hi:[0,1]
	v_lshlrev_b32_e32 v126, 16, v25
	v_and_b32_e32 v127, 0xffff0000, v25
	v_lshlrev_b32_e32 v90, 16, v24
	v_and_b32_e32 v91, 0xffff0000, v24
	v_pk_add_f32 v[92:93], v[92:93], v[126:127]
	v_pk_add_f32 v[24:25], v[146:147], v[138:139] neg_lo:[0,1] neg_hi:[0,1]
	v_pk_fma_f32 v[128:129], v[82:83], v[92:93], v[126:127] op_sel_hi:[0,1,1] neg_lo:[0,0,1] neg_hi:[0,0,1]
	v_pk_add_f32 v[138:139], v[24:25], v[136:137]
	v_pk_add_f32 v[24:25], v[156:157], v[148:149] neg_lo:[0,1] neg_hi:[0,1]
	v_lshlrev_b32_e32 v148, 16, v27
	v_and_b32_e32 v149, 0xffff0000, v27
	v_pk_add_f32 v[156:157], v[24:25], v[148:149]
	v_cvt_pk_bf16_f32 v25, v128, v129
	v_div_scale_f32 v128, s[46:47], v69, v69, 1.0
	v_pk_add_f32 v[84:85], v[84:85], v[90:91]
	v_rcp_f32_e32 v129, v128
	v_pk_fma_f32 v[86:87], v[82:83], v[84:85], v[90:91] op_sel_hi:[0,1,1] neg_lo:[0,0,1] neg_hi:[0,0,1]
	v_pk_fma_f32 v[146:147], v[82:83], v[138:139], v[136:137] op_sel_hi:[0,1,1] neg_lo:[0,0,1] neg_hi:[0,0,1]
	v_pk_fma_f32 v[82:83], v[82:83], v[156:157], v[148:149] op_sel_hi:[0,1,1] neg_lo:[0,0,1] neg_hi:[0,0,1]
	v_cvt_pk_bf16_f32 v27, v82, v83
	v_lshlrev_b64 v[82:83], 12, v[80:81]
	v_cvt_pk_bf16_f32 v24, v86, v87
	v_cvt_pk_bf16_f32 v26, v146, v147
	v_lshl_add_u64 v[86:87], v[62:63], 0, v[82:83]
	global_store_dwordx4 v[86:87], v[24:27], off offset:512
	s_waitcnt vmcnt(18)
	v_lshlrev_b32_e32 v146, 16, v19
	v_and_b32_e32 v147, 0xffff0000, v19
	v_fma_f32 v24, -v128, v129, 1.0
	v_fmac_f32_e32 v129, v24, v129
	v_div_scale_f32 v24, vcc, 1.0, v69, 1.0
	v_mul_f32_e32 v25, v24, v129
	v_fma_f32 v26, -v128, v25, v24
	v_fmac_f32_e32 v25, v26, v129
	v_fma_f32 v24, -v128, v25, v24
	v_pk_add_f32 v[26:27], v[84:85], v[106:107] neg_lo:[0,1] neg_hi:[0,1]
	v_pk_add_f32 v[84:85], v[92:93], v[130:131] neg_lo:[0,1] neg_hi:[0,1]
	v_lshlrev_b32_e32 v130, 16, v18
	v_and_b32_e32 v131, 0xffff0000, v18
	v_min_i32_e32 v18, 3, v119
	v_div_fmas_f32 v24, v24, v129, v25
	v_add_u32_e32 v18, 1, v18
	v_div_fixup_f32 v24, v24, v69, 1.0
	v_cvt_f32_i32_e32 v69, v18
	v_lshlrev_b32_e32 v106, 16, v16
	v_and_b32_e32 v107, 0xffff0000, v16
	v_pk_add_f32 v[26:27], v[26:27], v[106:107]
	v_lshlrev_b32_e32 v128, 16, v17
	v_and_b32_e32 v129, 0xffff0000, v17
	v_pk_add_f32 v[16:17], v[138:139], v[140:141] neg_lo:[0,1] neg_hi:[0,1]
	v_pk_fma_f32 v[82:83], v[24:25], v[26:27], v[106:107] op_sel_hi:[0,1,1] neg_lo:[0,0,1] neg_hi:[0,0,1]
	v_pk_add_f32 v[138:139], v[16:17], v[130:131]
	v_pk_add_f32 v[16:17], v[156:157], v[150:151] neg_lo:[0,1] neg_hi:[0,1]
	v_pk_add_f32 v[92:93], v[84:85], v[128:129]
	v_pk_add_f32 v[150:151], v[16:17], v[146:147]
	v_cvt_pk_bf16_f32 v16, v82, v83
	v_div_scale_f32 v82, s[46:47], v69, v69, 1.0
	v_rcp_f32_e32 v83, v82
	v_pk_fma_f32 v[84:85], v[24:25], v[92:93], v[128:129] op_sel_hi:[0,1,1] neg_lo:[0,0,1] neg_hi:[0,0,1]
	v_pk_fma_f32 v[140:141], v[24:25], v[138:139], v[130:131] op_sel_hi:[0,1,1] neg_lo:[0,0,1] neg_hi:[0,0,1]
	v_pk_fma_f32 v[24:25], v[24:25], v[150:151], v[146:147] op_sel_hi:[0,1,1] neg_lo:[0,0,1] neg_hi:[0,0,1]
	v_cvt_pk_bf16_f32 v19, v24, v25
	v_lshlrev_b64 v[24:25], 12, v[78:79]
	v_cvt_pk_bf16_f32 v17, v84, v85
	v_cvt_pk_bf16_f32 v18, v140, v141
	v_lshl_add_u64 v[84:85], v[62:63], 0, v[24:25]
	global_store_dwordx4 v[84:85], v[16:19], off offset:512
	v_pk_add_f32 v[140:141], v[150:151], v[152:153] neg_lo:[0,1] neg_hi:[0,1]
	s_nop 0
	v_fma_f32 v16, -v82, v83, 1.0
	v_fmac_f32_e32 v83, v16, v83
	v_div_scale_f32 v16, vcc, 1.0, v69, 1.0
	v_mul_f32_e32 v17, v16, v83
	v_fma_f32 v18, -v82, v17, v16
	v_fmac_f32_e32 v17, v18, v83
	v_fma_f32 v16, -v82, v17, v16
	v_div_fmas_f32 v16, v16, v83, v17
	v_pk_add_f32 v[18:19], v[26:27], v[108:109] neg_lo:[0,1] neg_hi:[0,1]
	s_waitcnt vmcnt(12)
	v_lshlrev_b32_e32 v108, 16, v94
	v_and_b32_e32 v109, 0xffff0000, v94
	v_div_fixup_f32 v16, v16, v69, 1.0
	v_pk_add_f32 v[24:25], v[18:19], v[108:109]
	v_pk_add_f32 v[26:27], v[92:93], v[132:133] neg_lo:[0,1] neg_hi:[0,1]
	v_lshlrev_b32_e32 v132, 16, v95
	v_and_b32_e32 v133, 0xffff0000, v95
	v_pk_add_f32 v[92:93], v[138:139], v[142:143] neg_lo:[0,1] neg_hi:[0,1]
	v_lshlrev_b32_e32 v138, 16, v96
	v_and_b32_e32 v139, 0xffff0000, v96
	v_lshlrev_b32_e32 v142, 16, v97
	v_and_b32_e32 v143, 0xffff0000, v97
	v_pk_fma_f32 v[18:19], v[16:17], v[24:25], v[108:109] op_sel_hi:[0,1,1] neg_lo:[0,0,1] neg_hi:[0,0,1]
	v_pk_add_f32 v[26:27], v[26:27], v[132:133]
	v_pk_add_f32 v[92:93], v[92:93], v[138:139]
	v_pk_add_f32 v[96:97], v[140:141], v[142:143]
	v_pk_fma_f32 v[82:83], v[16:17], v[26:27], v[132:133] op_sel_hi:[0,1,1] neg_lo:[0,0,1] neg_hi:[0,0,1]
	v_pk_fma_f32 v[94:95], v[16:17], v[92:93], v[138:139] op_sel_hi:[0,1,1] neg_lo:[0,0,1] neg_hi:[0,0,1]
	v_pk_fma_f32 v[140:141], v[16:17], v[96:97], v[142:143] op_sel_hi:[0,1,1] neg_lo:[0,0,1] neg_hi:[0,0,1]
	v_cvt_pk_bf16_f32 v16, v18, v19
	v_min_i32_e32 v18, 3, v118
	v_add_u32_e32 v18, 1, v18
	v_cvt_f32_i32_e32 v69, v18
	v_cvt_pk_bf16_f32 v18, v94, v95
	v_cvt_pk_bf16_f32 v17, v82, v83
	v_lshlrev_b64 v[82:83], 12, v[76:77]
	v_div_scale_f32 v94, s[46:47], v69, v69, 1.0
	v_rcp_f32_e32 v95, v94
	v_cvt_pk_bf16_f32 v19, v140, v141
	v_lshl_add_u64 v[82:83], v[62:63], 0, v[82:83]
	global_store_dwordx4 v[82:83], v[16:19], off offset:512
	v_pk_add_f32 v[92:93], v[92:93], v[144:145] neg_lo:[0,1] neg_hi:[0,1]
	v_pk_add_f32 v[96:97], v[96:97], v[154:155] neg_lo:[0,1] neg_hi:[0,1]
	v_fma_f32 v16, -v94, v95, 1.0
	v_fmac_f32_e32 v95, v16, v95
	v_div_scale_f32 v16, vcc, 1.0, v69, 1.0
	v_mul_f32_e32 v17, v16, v95
	v_fma_f32 v18, -v94, v17, v16
	v_fmac_f32_e32 v17, v18, v95
	v_fma_f32 v16, -v94, v17, v16
	v_div_fmas_f32 v16, v16, v95, v17
	v_pk_add_f32 v[18:19], v[24:25], v[110:111] neg_lo:[0,1] neg_hi:[0,1]
	s_waitcnt vmcnt(11)
	v_lshlrev_b32_e32 v24, 16, v98
	v_and_b32_e32 v25, 0xffff0000, v98
	v_div_fixup_f32 v16, v16, v69, 1.0
	v_pk_add_f32 v[94:95], v[18:19], v[24:25]
	v_lshlrev_b32_e32 v98, 16, v100
	v_pk_fma_f32 v[18:19], v[16:17], v[94:95], v[24:25] op_sel_hi:[0,1,1] neg_lo:[0,0,1] neg_hi:[0,0,1]
	v_pk_add_f32 v[24:25], v[26:27], v[134:135] neg_lo:[0,1] neg_hi:[0,1]
	v_lshlrev_b32_e32 v26, 16, v99
	v_and_b32_e32 v27, 0xffff0000, v99
	v_and_b32_e32 v99, 0xffff0000, v100
	v_lshlrev_b32_e32 v100, 16, v101
	v_and_b32_e32 v101, 0xffff0000, v101
	v_pk_add_f32 v[24:25], v[24:25], v[26:27]
	v_pk_add_f32 v[92:93], v[92:93], v[98:99]
	v_pk_add_f32 v[96:97], v[96:97], v[100:101]
	v_pk_fma_f32 v[26:27], v[16:17], v[24:25], v[26:27] op_sel_hi:[0,1,1] neg_lo:[0,0,1] neg_hi:[0,0,1]
	v_pk_fma_f32 v[98:99], v[16:17], v[92:93], v[98:99] op_sel_hi:[0,1,1] neg_lo:[0,0,1] neg_hi:[0,0,1]
	v_pk_fma_f32 v[100:101], v[16:17], v[96:97], v[100:101] op_sel_hi:[0,1,1] neg_lo:[0,0,1] neg_hi:[0,0,1]
	v_cvt_pk_bf16_f32 v16, v18, v19
	v_min_i32_e32 v18, 3, v117
	v_add_u32_e32 v18, 1, v18
	v_cvt_f32_i32_e32 v69, v18
	v_cvt_pk_bf16_f32 v18, v98, v99
	v_cvt_pk_bf16_f32 v17, v26, v27
	v_lshlrev_b64 v[26:27], 12, v[74:75]
	v_div_scale_f32 v98, s[46:47], v69, v69, 1.0
	v_rcp_f32_e32 v99, v98
	v_cvt_pk_bf16_f32 v19, v100, v101
	v_lshl_add_u64 v[26:27], v[62:63], 0, v[26:27]
	global_store_dwordx4 v[26:27], v[16:19], off offset:512
	v_pk_add_f32 v[24:25], v[24:25], v[126:127] neg_lo:[0,1] neg_hi:[0,1]
	s_nop 0
	v_fma_f32 v16, -v98, v99, 1.0
	v_fmac_f32_e32 v99, v16, v99
	v_div_scale_f32 v16, vcc, 1.0, v69, 1.0
	v_mul_f32_e32 v17, v16, v99
	v_fma_f32 v18, -v98, v17, v16
	v_fmac_f32_e32 v17, v18, v99
	v_fma_f32 v16, -v98, v17, v16
	v_div_fmas_f32 v16, v16, v99, v17
	v_pk_add_f32 v[18:19], v[94:95], v[90:91] neg_lo:[0,1] neg_hi:[0,1]
	s_waitcnt vmcnt(10)
	v_lshlrev_b32_e32 v90, 16, v102
	v_and_b32_e32 v91, 0xffff0000, v102
	v_div_fixup_f32 v16, v16, v69, 1.0
	v_pk_add_f32 v[94:95], v[18:19], v[90:91]
	s_nop 0
	v_pk_fma_f32 v[18:19], v[16:17], v[94:95], v[90:91] op_sel_hi:[0,1,1] neg_lo:[0,0,1] neg_hi:[0,0,1]
	v_lshlrev_b32_e32 v90, 16, v103
	v_and_b32_e32 v91, 0xffff0000, v103
	v_pk_add_f32 v[24:25], v[24:25], v[90:91]
	s_nop 0
	v_pk_fma_f32 v[98:99], v[16:17], v[24:25], v[90:91] op_sel_hi:[0,1,1] neg_lo:[0,0,1] neg_hi:[0,0,1]
	v_pk_add_f32 v[90:91], v[92:93], v[136:137] neg_lo:[0,1] neg_hi:[0,1]
	v_lshlrev_b32_e32 v92, 16, v104
	v_and_b32_e32 v93, 0xffff0000, v104
	v_pk_add_f32 v[110:111], v[90:91], v[92:93]
	v_pk_add_f32 v[90:91], v[96:97], v[148:149] neg_lo:[0,1] neg_hi:[0,1]
	v_lshlrev_b32_e32 v96, 16, v105
	v_and_b32_e32 v97, 0xffff0000, v105
	v_pk_add_f32 v[126:127], v[90:91], v[96:97]
	v_cvt_pk_bf16_f32 v90, v18, v19
	v_min_i32_e32 v18, 3, v116
	v_add_u32_e32 v18, 1, v18
	v_cvt_f32_i32_e32 v69, v18
	v_pk_fma_f32 v[92:93], v[16:17], v[110:111], v[92:93] op_sel_hi:[0,1,1] neg_lo:[0,0,1] neg_hi:[0,0,1]
	v_pk_fma_f32 v[16:17], v[16:17], v[126:127], v[96:97] op_sel_hi:[0,1,1] neg_lo:[0,0,1] neg_hi:[0,0,1]
	v_cvt_pk_bf16_f32 v92, v92, v93
	v_div_scale_f32 v96, s[46:47], v69, v69, 1.0
	v_rcp_f32_e32 v97, v96
	v_cvt_pk_bf16_f32 v93, v16, v17
	v_lshlrev_b64 v[16:17], 12, v[72:73]
	v_lshl_add_u64 v[18:19], v[62:63], 0, v[16:17]
	v_fma_f32 v16, -v96, v97, 1.0
	v_fmac_f32_e32 v97, v16, v97
	v_div_scale_f32 v16, vcc, 1.0, v69, 1.0
	v_cvt_pk_bf16_f32 v91, v98, v99
	v_mul_f32_e32 v17, v16, v97
	global_store_dwordx4 v[18:19], v[90:93], off offset:512
	v_pk_add_f32 v[24:25], v[24:25], v[128:129] neg_lo:[0,1] neg_hi:[0,1]
	v_add_u32_e32 v136, -7, v66
	v_fma_f32 v90, -v96, v17, v16
	v_fmac_f32_e32 v17, v90, v97
	v_fma_f32 v16, -v96, v17, v16
	v_div_fmas_f32 v16, v16, v97, v17
	s_waitcnt vmcnt(9)
	v_lshlrev_b32_e32 v92, 16, v56
	v_and_b32_e32 v93, 0xffff0000, v56
	v_lshlrev_b32_e32 v56, 16, v57
	v_and_b32_e32 v57, 0xffff0000, v57
	v_div_fixup_f32 v16, v16, v69, 1.0
	v_pk_add_f32 v[128:129], v[24:25], v[56:57]
	v_pk_add_f32 v[90:91], v[94:95], v[106:107] neg_lo:[0,1] neg_hi:[0,1]
	v_pk_fma_f32 v[24:25], v[16:17], v[128:129], v[56:57] op_sel_hi:[0,1,1] neg_lo:[0,0,1] neg_hi:[0,0,1]
	v_max_i32_e32 v56, s8, v136
	v_ashrrev_i32_e32 v57, 31, v56
	v_pk_add_f32 v[106:107], v[90:91], v[92:93]
	v_lshlrev_b64 v[56:57], 12, v[56:57]
	v_pk_fma_f32 v[134:135], v[16:17], v[106:107], v[92:93] op_sel_hi:[0,1,1] neg_lo:[0,0,1] neg_hi:[0,0,1]
	v_lshl_add_u64 v[56:57], v[64:65], 0, v[56:57]
	v_add_u32_e32 v17, -6, v66
	global_load_dwordx4 v[90:93], v[56:57], off offset:1024
	v_max_i32_e32 v56, s8, v17
	v_ashrrev_i32_e32 v57, 31, v56
	v_lshlrev_b64 v[56:57], 12, v[56:57]
	v_lshl_add_u64 v[56:57], v[64:65], 0, v[56:57]
	v_add_u32_e32 v17, -5, v66
	global_load_dwordx4 v[94:97], v[56:57], off offset:1024
	v_max_i32_e32 v56, s8, v17
	v_ashrrev_i32_e32 v57, 31, v56
	v_lshlrev_b64 v[56:57], 12, v[56:57]
	v_lshl_add_u64 v[56:57], v[64:65], 0, v[56:57]
	v_add_u32_e32 v17, -4, v66
	global_load_dwordx4 v[98:101], v[56:57], off offset:1024
	v_max_i32_e32 v56, s8, v17
	v_ashrrev_i32_e32 v57, 31, v56
	v_lshlrev_b64 v[56:57], 12, v[56:57]
	v_lshl_add_u64 v[56:57], v[64:65], 0, v[56:57]
	global_load_dwordx4 v[102:105], v[56:57], off offset:1024
	v_pk_add_f32 v[56:57], v[110:111], v[130:131] neg_lo:[0,1] neg_hi:[0,1]
	v_lshlrev_b32_e32 v110, 16, v58
	v_and_b32_e32 v111, 0xffff0000, v58
	v_pk_add_f32 v[130:131], v[56:57], v[110:111]
	v_pk_add_f32 v[56:57], v[126:127], v[146:147] neg_lo:[0,1] neg_hi:[0,1]
	v_lshlrev_b32_e32 v58, 16, v59
	v_and_b32_e32 v59, 0xffff0000, v59
	v_pk_add_f32 v[126:127], v[56:57], v[58:59]
	v_cvt_pk_bf16_f32 v57, v24, v25
	v_min_i32_e32 v24, 3, v60
	v_add_u32_e32 v24, 1, v24
	v_cvt_f32_i32_e32 v69, v24
	v_pk_fma_f32 v[110:111], v[16:17], v[130:131], v[110:111] op_sel_hi:[0,1,1] neg_lo:[0,0,1] neg_hi:[0,0,1]
	v_pk_fma_f32 v[16:17], v[16:17], v[126:127], v[58:59] op_sel_hi:[0,1,1] neg_lo:[0,0,1] neg_hi:[0,0,1]
	v_cvt_pk_bf16_f32 v58, v110, v111
	v_div_scale_f32 v110, s[8:9], v69, v69, 1.0
	v_rcp_f32_e32 v111, v110
	v_cvt_pk_bf16_f32 v59, v16, v17
	v_lshlrev_b64 v[16:17], 12, v[70:71]
	v_lshl_add_u64 v[24:25], v[62:63], 0, v[16:17]
	v_fma_f32 v16, -v110, v111, 1.0
	v_fmac_f32_e32 v111, v16, v111
	v_div_scale_f32 v16, vcc, 1.0, v69, 1.0
	v_cvt_pk_bf16_f32 v56, v134, v135
	v_mul_f32_e32 v17, v16, v111
	global_store_dwordx4 v[24:25], v[56:59], off offset:512
	s_nop 1
	v_fma_f32 v56, -v110, v17, v16
	v_fmac_f32_e32 v17, v56, v111
	v_fma_f32 v16, -v110, v17, v16
	v_div_fmas_f32 v16, v16, v111, v17
	v_pk_add_f32 v[56:57], v[106:107], v[108:109] neg_lo:[0,1] neg_hi:[0,1]
	s_waitcnt vmcnt(12)
	v_lshlrev_b32_e32 v58, 16, v52
	v_and_b32_e32 v59, 0xffff0000, v52
	v_div_fixup_f32 v16, v16, v69, 1.0
	v_pk_add_f32 v[56:57], v[56:57], v[58:59]
	v_lshlrev_b32_e32 v52, 16, v53
	v_pk_fma_f32 v[56:57], v[16:17], v[56:57], v[58:59] op_sel_hi:[0,1,1] neg_lo:[0,0,1] neg_hi:[0,0,1]
	v_pk_add_f32 v[58:59], v[128:129], v[132:133] neg_lo:[0,1] neg_hi:[0,1]
	v_and_b32_e32 v53, 0xffff0000, v53
	v_pk_add_f32 v[58:59], v[58:59], v[52:53]
	v_lshlrev_b32_e32 v106, 16, v54
	v_pk_fma_f32 v[58:59], v[16:17], v[58:59], v[52:53] op_sel_hi:[0,1,1] neg_lo:[0,0,1] neg_hi:[0,0,1]
	v_pk_add_f32 v[52:53], v[130:131], v[138:139] neg_lo:[0,1] neg_hi:[0,1]
	v_and_b32_e32 v107, 0xffff0000, v54
	v_pk_add_f32 v[52:53], v[52:53], v[106:107]
	v_lshlrev_b32_e32 v54, 16, v55
	v_pk_fma_f32 v[106:107], v[16:17], v[52:53], v[106:107] op_sel_hi:[0,1,1] neg_lo:[0,0,1] neg_hi:[0,0,1]
	v_pk_add_f32 v[52:53], v[126:127], v[142:143] neg_lo:[0,1] neg_hi:[0,1]
	v_and_b32_e32 v55, 0xffff0000, v55
	v_pk_add_f32 v[52:53], v[52:53], v[54:55]
	v_ashrrev_i32_e32 v69, 31, v68
	v_pk_fma_f32 v[16:17], v[16:17], v[52:53], v[54:55] op_sel_hi:[0,1,1] neg_lo:[0,0,1] neg_hi:[0,0,1]
	v_cvt_pk_bf16_f32 v55, v16, v17
	v_lshlrev_b64 v[16:17], 12, v[68:69]
	v_cvt_pk_bf16_f32 v52, v56, v57
	v_cvt_pk_bf16_f32 v53, v58, v59
	v_cvt_pk_bf16_f32 v54, v106, v107
	v_lshl_add_u64 v[16:17], v[62:63], 0, v[16:17]
	global_store_dwordx4 v[16:17], v[52:55], off offset:512
	s_nop 1
	v_add_u32_e32 v52, s10, v136
	v_cmp_lt_i32_e32 vcc, -1, v52
	s_waitcnt vmcnt(5)
	s_nop 0
	v_cndmask_b32_e32 v53, 0, v93, vcc
	v_cndmask_b32_e32 v54, 0, v92, vcc
	v_cndmask_b32_e32 v55, 0, v91, vcc
	v_cndmask_b32_e32 v56, 0, v90, vcc
	v_cmp_lt_i32_e32 vcc, -2, v52
	v_lshlrev_b32_e32 v130, 16, v56
	v_and_b32_e32 v131, 0xffff0000, v56
	s_waitcnt vmcnt(4)
	v_cndmask_b32_e32 v57, 0, v97, vcc
	v_cndmask_b32_e32 v58, 0, v96, vcc
	v_cndmask_b32_e32 v59, 0, v95, vcc
	v_cndmask_b32_e32 v69, 0, v94, vcc
	v_cmp_lt_i32_e32 vcc, -3, v52
	v_lshlrev_b32_e32 v106, 16, v69
	v_and_b32_e32 v107, 0xffff0000, v69
	s_waitcnt vmcnt(3)
	v_cndmask_b32_e32 v94, 0, v101, vcc
	v_cndmask_b32_e32 v90, 0, v100, vcc
	v_cndmask_b32_e32 v91, 0, v99, vcc
	v_cndmask_b32_e32 v92, 0, v98, vcc
	v_cmp_lt_i32_e32 vcc, -4, v52
	v_lshlrev_b32_e32 v96, 16, v92
	v_and_b32_e32 v97, 0xffff0000, v92
	s_waitcnt vmcnt(2)
	v_cndmask_b32_e32 v95, 0, v105, vcc
	v_cndmask_b32_e32 v99, 0, v104, vcc
	v_cndmask_b32_e32 v93, 0, v103, vcc
	v_cndmask_b32_e32 v98, 0, v102, vcc
	v_cmp_lt_i32_e32 vcc, -5, v52
	v_lshlrev_b32_e32 v102, 16, v59
	v_and_b32_e32 v103, 0xffff0000, v59
	v_cndmask_b32_e32 v127, 0, v51, vcc
	v_cndmask_b32_e32 v110, 0, v50, vcc
	v_cndmask_b32_e32 v49, 0, v49, vcc
	v_cndmask_b32_e32 v48, 0, v48, vcc
	v_cmp_lt_i32_e32 vcc, -6, v52
	v_lshlrev_b32_e32 v104, 16, v58
	v_and_b32_e32 v105, 0xffff0000, v58
	v_cndmask_b32_e32 v152, 0, v47, vcc
	v_cndmask_b32_e32 v111, 0, v46, vcc
	v_cndmask_b32_e32 v140, 0, v45, vcc
	v_cndmask_b32_e32 v45, 0, v44, vcc
	v_cmp_lt_i32_e32 vcc, -7, v52
	v_lshlrev_b32_e32 v58, 16, v98
	v_and_b32_e32 v59, 0xffff0000, v98
	v_cndmask_b32_e32 v46, 0, v40, vcc
	v_min_i32_e32 v40, 7, v122
	v_add_u32_e32 v40, 1, v40
	v_cvt_f32_i32_e32 v40, v40
	v_cndmask_b32_e32 v52, 0, v41, vcc
	v_cndmask_b32_e32 v146, 0, v42, vcc
	v_cndmask_b32_e32 v154, 0, v43, vcc
	v_div_scale_f32 v41, s[8:9], v40, v40, 1.0
	v_rcp_f32_e32 v42, v41
	v_lshlrev_b32_e32 v50, 16, v48
	v_and_b32_e32 v51, 0xffff0000, v48
	v_lshlrev_b32_e32 v132, 16, v55
	v_fma_f32 v43, -v41, v42, 1.0
	v_fmac_f32_e32 v42, v43, v42
	v_div_scale_f32 v43, vcc, 1.0, v40, 1.0
	v_mul_f32_e32 v44, v43, v42
	v_fma_f32 v47, -v41, v44, v43
	v_fmac_f32_e32 v44, v47, v42
	v_fma_f32 v41, -v41, v44, v43
	v_div_fmas_f32 v41, v41, v42, v44
	v_div_fixup_f32 v126, v41, v40, 1.0
	v_pk_add_f32 v[40:41], v[130:131], 0 op_sel_hi:[1,0]
	v_lshlrev_b32_e32 v44, 16, v45
	v_pk_add_f32 v[40:41], v[40:41], v[106:107]
	v_and_b32_e32 v45, 0xffff0000, v45
	v_pk_add_f32 v[40:41], v[40:41], v[96:97]
	v_and_b32_e32 v133, 0xffff0000, v55
	v_pk_add_f32 v[40:41], v[40:41], v[58:59]
	v_and_b32_e32 v47, 0xffff0000, v36
	v_pk_add_f32 v[40:41], v[40:41], v[50:51]
	v_lshlrev_b32_e32 v108, 16, v91
	v_pk_add_f32 v[42:43], v[40:41], v[44:45]
	v_lshlrev_b32_e32 v40, 16, v46
	v_and_b32_e32 v41, 0xffff0000, v46
	v_pk_add_f32 v[42:43], v[42:43], v[40:41]
	v_lshlrev_b32_e32 v46, 16, v36
	v_pk_add_f32 v[138:139], v[42:43], v[46:47]
	v_pk_add_f32 v[42:43], v[132:133], 0 op_sel_hi:[1,0]
	v_and_b32_e32 v109, 0xffff0000, v91
	v_pk_add_f32 v[42:43], v[42:43], v[102:103]
	v_lshlrev_b32_e32 v92, 16, v93
	v_pk_add_f32 v[42:43], v[42:43], v[108:109]
	v_and_b32_e32 v93, 0xffff0000, v93
	v_lshlrev_b32_e32 v134, 16, v54
	v_and_b32_e32 v135, 0xffff0000, v54
	v_pk_add_f32 v[42:43], v[42:43], v[92:93]
	v_lshlrev_b32_e32 v54, 16, v49
	v_and_b32_e32 v55, 0xffff0000, v49
	v_pk_fma_f32 v[128:129], v[126:127], v[138:139], v[46:47] op_sel_hi:[0,1,1] neg_lo:[0,0,1] neg_hi:[0,0,1]
	v_pk_add_f32 v[42:43], v[42:43], v[54:55]
	v_lshlrev_b32_e32 v46, 16, v140
	v_and_b32_e32 v47, 0xffff0000, v140
	v_pk_add_f32 v[48:49], v[42:43], v[46:47]
	v_lshlrev_b32_e32 v42, 16, v52
	v_and_b32_e32 v43, 0xffff0000, v52
	v_pk_add_f32 v[48:49], v[48:49], v[42:43]
	v_lshlrev_b32_e32 v36, 16, v37
	v_and_b32_e32 v37, 0xffff0000, v37
	v_pk_add_f32 v[140:141], v[48:49], v[36:37]
	v_lshlrev_b32_e32 v144, 16, v90
	v_pk_fma_f32 v[142:143], v[126:127], v[140:141], v[36:37] op_sel_hi:[0,1,1] neg_lo:[0,0,1] neg_hi:[0,0,1]
	v_pk_add_f32 v[36:37], v[134:135], 0 op_sel_hi:[1,0]
	v_and_b32_e32 v145, 0xffff0000, v90
	v_pk_add_f32 v[36:37], v[36:37], v[104:105]
	v_lshlrev_b32_e32 v98, 16, v99
	v_pk_add_f32 v[36:37], v[36:37], v[144:145]
	v_and_b32_e32 v99, 0xffff0000, v99
	v_pk_add_f32 v[36:37], v[36:37], v[98:99]
	v_lshlrev_b32_e32 v90, 16, v110
	v_and_b32_e32 v91, 0xffff0000, v110
	v_lshlrev_b32_e32 v136, 16, v53
	v_and_b32_e32 v137, 0xffff0000, v53
	v_pk_add_f32 v[36:37], v[36:37], v[90:91]
	v_lshlrev_b32_e32 v52, 16, v111
	v_and_b32_e32 v53, 0xffff0000, v111
	v_pk_add_f32 v[48:49], v[36:37], v[52:53]
	v_lshlrev_b32_e32 v36, 16, v146
	v_and_b32_e32 v37, 0xffff0000, v146
	v_lshlrev_b32_e32 v100, 16, v57
	v_and_b32_e32 v101, 0xffff0000, v57
	v_pk_add_f32 v[48:49], v[48:49], v[36:37]
	v_lshlrev_b32_e32 v56, 16, v38
	v_and_b32_e32 v57, 0xffff0000, v38
	v_pk_add_f32 v[146:147], v[48:49], v[56:57]
	v_pk_add_f32 v[48:49], v[136:137], 0 op_sel_hi:[1,0]
	v_lshlrev_b32_e32 v150, 16, v94
	v_pk_add_f32 v[48:49], v[48:49], v[100:101]
	v_and_b32_e32 v151, 0xffff0000, v94
	v_pk_add_f32 v[48:49], v[48:49], v[150:151]
	v_lshlrev_b32_e32 v110, 16, v95
	v_and_b32_e32 v111, 0xffff0000, v95
	v_min_i32_e32 v69, 7, v121
	v_pk_add_f32 v[48:49], v[48:49], v[110:111]
	v_lshlrev_b32_e32 v94, 16, v127
	v_and_b32_e32 v95, 0xffff0000, v127
	v_add_u32_e32 v69, 1, v69
	v_pk_fma_f32 v[148:149], v[126:127], v[146:147], v[56:57] op_sel_hi:[0,1,1] neg_lo:[0,0,1] neg_hi:[0,0,1]
	v_pk_add_f32 v[48:49], v[48:49], v[94:95]
	v_lshlrev_b32_e32 v56, 16, v152
	v_and_b32_e32 v57, 0xffff0000, v152
	v_cvt_f32_i32_e32 v69, v69
	v_pk_add_f32 v[152:153], v[48:49], v[56:57]
	v_lshlrev_b32_e32 v48, 16, v154
	v_and_b32_e32 v49, 0xffff0000, v154
	v_pk_add_f32 v[152:153], v[152:153], v[48:49]
	v_lshlrev_b32_e32 v38, 16, v39
	v_and_b32_e32 v39, 0xffff0000, v39
	v_pk_add_f32 v[152:153], v[152:153], v[38:39]
	s_nop 0
	v_pk_fma_f32 v[38:39], v[126:127], v[152:153], v[38:39] op_sel_hi:[0,1,1] neg_lo:[0,0,1] neg_hi:[0,0,1]
	v_cvt_pk_bf16_f32 v127, v142, v143
	v_div_scale_f32 v142, s[8:9], v69, v69, 1.0
	v_rcp_f32_e32 v143, v142
	v_cvt_pk_bf16_f32 v126, v128, v129
	v_cvt_pk_bf16_f32 v129, v38, v39
	v_cvt_pk_bf16_f32 v128, v148, v149
	v_fma_f32 v38, -v142, v143, 1.0
	v_fmac_f32_e32 v143, v38, v143
	v_div_scale_f32 v38, vcc, 1.0, v69, 1.0
	v_mul_f32_e32 v39, v38, v143
	global_store_dwordx4 v[88:89], v[126:129], off offset:1024
	v_fma_f32 v88, -v142, v39, v38
	v_fmac_f32_e32 v39, v88, v143
	v_fma_f32 v38, -v142, v39, v38
	v_div_fmas_f32 v38, v38, v143, v39
	v_lshlrev_b32_e32 v126, 16, v32
	v_and_b32_e32 v127, 0xffff0000, v32
	v_pk_add_f32 v[128:129], v[140:141], v[132:133] neg_lo:[0,1] neg_hi:[0,1]
	v_lshlrev_b32_e32 v32, 16, v33
	v_and_b32_e32 v33, 0xffff0000, v33
	v_div_fixup_f32 v38, v38, v69, 1.0
	v_pk_add_f32 v[128:129], v[128:129], v[32:33]
	v_pk_add_f32 v[88:89], v[138:139], v[130:131] neg_lo:[0,1] neg_hi:[0,1]
	v_pk_fma_f32 v[130:131], v[38:39], v[128:129], v[32:33] op_sel_hi:[0,1,1] neg_lo:[0,0,1] neg_hi:[0,0,1]
	v_pk_add_f32 v[32:33], v[146:147], v[134:135] neg_lo:[0,1] neg_hi:[0,1]
	v_lshlrev_b32_e32 v132, 16, v34
	v_and_b32_e32 v133, 0xffff0000, v34
	v_pk_add_f32 v[134:135], v[32:33], v[132:133]
	v_pk_add_f32 v[32:33], v[152:153], v[136:137] neg_lo:[0,1] neg_hi:[0,1]
	v_lshlrev_b32_e32 v34, 16, v35
	v_and_b32_e32 v35, 0xffff0000, v35
	v_pk_add_f32 v[136:137], v[32:33], v[34:35]
	v_min_i32_e32 v32, 7, v120
	v_add_u32_e32 v32, 1, v32
	v_cvt_f32_i32_e32 v69, v32
	v_pk_add_f32 v[88:89], v[88:89], v[126:127]
	v_pk_fma_f32 v[132:133], v[38:39], v[134:135], v[132:133] op_sel_hi:[0,1,1] neg_lo:[0,0,1] neg_hi:[0,0,1]
	v_pk_fma_f32 v[126:127], v[38:39], v[88:89], v[126:127] op_sel_hi:[0,1,1] neg_lo:[0,0,1] neg_hi:[0,0,1]
	v_cvt_pk_bf16_f32 v32, v126, v127
	v_div_scale_f32 v126, s[8:9], v69, v69, 1.0
	v_rcp_f32_e32 v127, v126
	v_pk_fma_f32 v[38:39], v[38:39], v[136:137], v[34:35] op_sel_hi:[0,1,1] neg_lo:[0,0,1] neg_hi:[0,0,1]
	v_cvt_pk_bf16_f32 v33, v130, v131
	v_cvt_pk_bf16_f32 v34, v132, v133
	v_cvt_pk_bf16_f32 v35, v38, v39
	global_store_dwordx4 v[86:87], v[32:35], off offset:1024
	v_lshlrev_b32_e32 v38, 16, v28
	v_and_b32_e32 v39, 0xffff0000, v28
	v_fma_f32 v32, -v126, v127, 1.0
	v_fmac_f32_e32 v127, v32, v127
	v_div_scale_f32 v32, vcc, 1.0, v69, 1.0
	v_mul_f32_e32 v33, v32, v127
	v_fma_f32 v34, -v126, v33, v32
	v_fmac_f32_e32 v33, v34, v127
	v_fma_f32 v32, -v126, v33, v32
	v_div_fmas_f32 v32, v32, v127, v33
	v_pk_add_f32 v[86:87], v[128:129], v[102:103] neg_lo:[0,1] neg_hi:[0,1]
	v_lshlrev_b32_e32 v28, 16, v29
	v_and_b32_e32 v29, 0xffff0000, v29
	v_div_fixup_f32 v32, v32, v69, 1.0
	v_pk_add_f32 v[86:87], v[86:87], v[28:29]
	v_pk_add_f32 v[34:35], v[88:89], v[106:107] neg_lo:[0,1] neg_hi:[0,1]
	v_pk_fma_f32 v[88:89], v[32:33], v[86:87], v[28:29] op_sel_hi:[0,1,1] neg_lo:[0,0,1] neg_hi:[0,0,1]
	v_pk_add_f32 v[28:29], v[134:135], v[104:105] neg_lo:[0,1] neg_hi:[0,1]
	v_lshlrev_b32_e32 v102, 16, v30
	v_and_b32_e32 v103, 0xffff0000, v30
	v_pk_add_f32 v[104:105], v[28:29], v[102:103]
	v_pk_add_f32 v[28:29], v[136:137], v[100:101] neg_lo:[0,1] neg_hi:[0,1]
	v_lshlrev_b32_e32 v30, 16, v31
	v_and_b32_e32 v31, 0xffff0000, v31
	v_pk_add_f32 v[100:101], v[28:29], v[30:31]
	v_min_i32_e32 v28, 7, v119
	v_add_u32_e32 v28, 1, v28
	v_cvt_f32_i32_e32 v69, v28
	v_pk_add_f32 v[34:35], v[34:35], v[38:39]
	v_pk_fma_f32 v[102:103], v[32:33], v[104:105], v[102:103] op_sel_hi:[0,1,1] neg_lo:[0,0,1] neg_hi:[0,0,1]
	v_pk_fma_f32 v[38:39], v[32:33], v[34:35], v[38:39] op_sel_hi:[0,1,1] neg_lo:[0,0,1] neg_hi:[0,0,1]
	v_cvt_pk_bf16_f32 v28, v38, v39
	v_div_scale_f32 v38, s[8:9], v69, v69, 1.0
	v_rcp_f32_e32 v39, v38
	v_pk_fma_f32 v[32:33], v[32:33], v[100:101], v[30:31] op_sel_hi:[0,1,1] neg_lo:[0,0,1] neg_hi:[0,0,1]
	v_cvt_pk_bf16_f32 v29, v88, v89
	v_cvt_pk_bf16_f32 v30, v102, v103
	v_cvt_pk_bf16_f32 v31, v32, v33
	global_store_dwordx4 v[84:85], v[28:31], off offset:1024
	v_lshlrev_b32_e32 v32, 16, v20
	v_and_b32_e32 v33, 0xffff0000, v20
	v_fma_f32 v28, -v38, v39, 1.0
	v_fmac_f32_e32 v39, v28, v39
	v_div_scale_f32 v28, vcc, 1.0, v69, 1.0
	v_mul_f32_e32 v29, v28, v39
	v_fma_f32 v30, -v38, v29, v28
	v_fmac_f32_e32 v29, v30, v39
	v_fma_f32 v28, -v38, v29, v28
	v_div_fmas_f32 v28, v28, v39, v29
	v_pk_add_f32 v[30:31], v[34:35], v[96:97] neg_lo:[0,1] neg_hi:[0,1]
	v_pk_add_f32 v[34:35], v[86:87], v[108:109] neg_lo:[0,1] neg_hi:[0,1]
	v_lshlrev_b32_e32 v20, 16, v21
	v_and_b32_e32 v21, 0xffff0000, v21
	v_div_fixup_f32 v28, v28, v69, 1.0
	v_pk_add_f32 v[34:35], v[34:35], v[20:21]
	v_lshlrev_b32_e32 v84, 16, v22
	v_pk_fma_f32 v[38:39], v[28:29], v[34:35], v[20:21] op_sel_hi:[0,1,1] neg_lo:[0,0,1] neg_hi:[0,0,1]
	v_pk_add_f32 v[20:21], v[104:105], v[144:145] neg_lo:[0,1] neg_hi:[0,1]
	v_and_b32_e32 v85, 0xffff0000, v22
	v_pk_add_f32 v[86:87], v[20:21], v[84:85]
	v_pk_add_f32 v[20:21], v[100:101], v[150:151] neg_lo:[0,1] neg_hi:[0,1]
	v_lshlrev_b32_e32 v22, 16, v23
	v_and_b32_e32 v23, 0xffff0000, v23
	v_pk_add_f32 v[88:89], v[20:21], v[22:23]
	v_min_i32_e32 v20, 7, v118
	v_add_u32_e32 v20, 1, v20
	v_cvt_f32_i32_e32 v69, v20
	v_pk_add_f32 v[30:31], v[30:31], v[32:33]
	v_pk_fma_f32 v[84:85], v[28:29], v[86:87], v[84:85] op_sel_hi:[0,1,1] neg_lo:[0,0,1] neg_hi:[0,0,1]
	v_pk_fma_f32 v[32:33], v[28:29], v[30:31], v[32:33] op_sel_hi:[0,1,1] neg_lo:[0,0,1] neg_hi:[0,0,1]
	v_cvt_pk_bf16_f32 v20, v32, v33
	v_div_scale_f32 v32, s[8:9], v69, v69, 1.0
	v_rcp_f32_e32 v33, v32
	v_pk_fma_f32 v[28:29], v[28:29], v[88:89], v[22:23] op_sel_hi:[0,1,1] neg_lo:[0,0,1] neg_hi:[0,0,1]
	v_cvt_pk_bf16_f32 v21, v38, v39
	v_cvt_pk_bf16_f32 v22, v84, v85
	v_cvt_pk_bf16_f32 v23, v28, v29
	global_store_dwordx4 v[82:83], v[20:23], off offset:1024
	v_lshlrev_b32_e32 v28, 16, v12
	v_and_b32_e32 v29, 0xffff0000, v12
	v_fma_f32 v20, -v32, v33, 1.0
	v_fmac_f32_e32 v33, v20, v33
	v_div_scale_f32 v20, vcc, 1.0, v69, 1.0
	v_mul_f32_e32 v21, v20, v33
	v_fma_f32 v22, -v32, v21, v20
	v_fmac_f32_e32 v21, v22, v33
	v_fma_f32 v20, -v32, v21, v20
	v_div_fmas_f32 v20, v20, v33, v21
	v_pk_add_f32 v[22:23], v[30:31], v[58:59] neg_lo:[0,1] neg_hi:[0,1]
	v_pk_add_f32 v[30:31], v[34:35], v[92:93] neg_lo:[0,1] neg_hi:[0,1]
	v_lshlrev_b32_e32 v12, 16, v13
	v_and_b32_e32 v13, 0xffff0000, v13
	v_div_fixup_f32 v20, v20, v69, 1.0
	v_pk_add_f32 v[30:31], v[30:31], v[12:13]
	v_lshlrev_b32_e32 v34, 16, v14
	v_pk_fma_f32 v[32:33], v[20:21], v[30:31], v[12:13] op_sel_hi:[0,1,1] neg_lo:[0,0,1] neg_hi:[0,0,1]
	v_pk_add_f32 v[12:13], v[86:87], v[98:99] neg_lo:[0,1] neg_hi:[0,1]
	v_and_b32_e32 v35, 0xffff0000, v14
	v_pk_add_f32 v[38:39], v[12:13], v[34:35]
	v_pk_add_f32 v[12:13], v[88:89], v[110:111] neg_lo:[0,1] neg_hi:[0,1]
	v_lshlrev_b32_e32 v14, 16, v15
	v_and_b32_e32 v15, 0xffff0000, v15
	v_pk_add_f32 v[58:59], v[12:13], v[14:15]
	v_min_i32_e32 v12, 7, v117
	v_add_u32_e32 v12, 1, v12
	v_cvt_f32_i32_e32 v69, v12
	v_pk_add_f32 v[22:23], v[22:23], v[28:29]
	v_pk_fma_f32 v[34:35], v[20:21], v[38:39], v[34:35] op_sel_hi:[0,1,1] neg_lo:[0,0,1] neg_hi:[0,0,1]
	v_pk_fma_f32 v[28:29], v[20:21], v[22:23], v[28:29] op_sel_hi:[0,1,1] neg_lo:[0,0,1] neg_hi:[0,0,1]
	v_cvt_pk_bf16_f32 v12, v28, v29
	v_div_scale_f32 v28, s[8:9], v69, v69, 1.0
	v_rcp_f32_e32 v29, v28
	v_pk_fma_f32 v[20:21], v[20:21], v[58:59], v[14:15] op_sel_hi:[0,1,1] neg_lo:[0,0,1] neg_hi:[0,0,1]
	v_cvt_pk_bf16_f32 v13, v32, v33
	v_cvt_pk_bf16_f32 v14, v34, v35
	v_cvt_pk_bf16_f32 v15, v20, v21
	global_store_dwordx4 v[26:27], v[12:15], off offset:1024
	v_lshlrev_b32_e32 v20, 16, v8
	v_and_b32_e32 v21, 0xffff0000, v8
	v_fma_f32 v12, -v28, v29, 1.0
	v_fmac_f32_e32 v29, v12, v29
	v_div_scale_f32 v12, vcc, 1.0, v69, 1.0
	v_mul_f32_e32 v13, v12, v29
	v_fma_f32 v14, -v28, v13, v12
	v_fmac_f32_e32 v13, v14, v29
	v_fma_f32 v12, -v28, v13, v12
	v_div_fmas_f32 v12, v12, v29, v13
	v_pk_add_f32 v[14:15], v[22:23], v[50:51] neg_lo:[0,1] neg_hi:[0,1]
	v_pk_add_f32 v[22:23], v[30:31], v[54:55] neg_lo:[0,1] neg_hi:[0,1]
	v_lshlrev_b32_e32 v8, 16, v9
	v_and_b32_e32 v9, 0xffff0000, v9
	v_div_fixup_f32 v12, v12, v69, 1.0
	v_pk_add_f32 v[22:23], v[22:23], v[8:9]
	v_lshlrev_b32_e32 v28, 16, v10
	v_pk_fma_f32 v[26:27], v[12:13], v[22:23], v[8:9] op_sel_hi:[0,1,1] neg_lo:[0,0,1] neg_hi:[0,0,1]
	v_pk_add_f32 v[8:9], v[38:39], v[90:91] neg_lo:[0,1] neg_hi:[0,1]
	v_and_b32_e32 v29, 0xffff0000, v10
	v_pk_add_f32 v[30:31], v[8:9], v[28:29]
	v_pk_add_f32 v[8:9], v[58:59], v[94:95] neg_lo:[0,1] neg_hi:[0,1]
	v_lshlrev_b32_e32 v10, 16, v11
	v_and_b32_e32 v11, 0xffff0000, v11
	v_pk_add_f32 v[32:33], v[8:9], v[10:11]
	v_min_i32_e32 v8, 7, v116
	v_add_u32_e32 v8, 1, v8
	v_cvt_f32_i32_e32 v34, v8
	v_pk_add_f32 v[14:15], v[14:15], v[20:21]
	v_pk_fma_f32 v[28:29], v[12:13], v[30:31], v[28:29] op_sel_hi:[0,1,1] neg_lo:[0,0,1] neg_hi:[0,0,1]
	v_pk_fma_f32 v[20:21], v[12:13], v[14:15], v[20:21] op_sel_hi:[0,1,1] neg_lo:[0,0,1] neg_hi:[0,0,1]
	v_cvt_pk_bf16_f32 v8, v20, v21
	v_div_scale_f32 v20, s[8:9], v34, v34, 1.0
	v_rcp_f32_e32 v21, v20
	v_pk_fma_f32 v[12:13], v[12:13], v[32:33], v[10:11] op_sel_hi:[0,1,1] neg_lo:[0,0,1] neg_hi:[0,0,1]
	v_cvt_pk_bf16_f32 v9, v26, v27
	v_cvt_pk_bf16_f32 v10, v28, v29
	v_cvt_pk_bf16_f32 v11, v12, v13
	global_store_dwordx4 v[18:19], v[8:11], off offset:1024
	v_lshlrev_b32_e32 v12, 16, v4
	v_and_b32_e32 v13, 0xffff0000, v4
	v_fma_f32 v8, -v20, v21, 1.0
	v_fmac_f32_e32 v21, v8, v21
	v_div_scale_f32 v8, vcc, 1.0, v34, 1.0
	v_mul_f32_e32 v9, v8, v21
	v_fma_f32 v10, -v20, v9, v8
	v_fmac_f32_e32 v9, v10, v21
	v_fma_f32 v8, -v20, v9, v8
	v_div_fmas_f32 v8, v8, v21, v9
	v_pk_add_f32 v[10:11], v[14:15], v[44:45] neg_lo:[0,1] neg_hi:[0,1]
	v_pk_add_f32 v[14:15], v[22:23], v[46:47] neg_lo:[0,1] neg_hi:[0,1]
	v_lshlrev_b32_e32 v4, 16, v5
	v_and_b32_e32 v5, 0xffff0000, v5
	v_div_fixup_f32 v8, v8, v34, 1.0
	v_pk_add_f32 v[14:15], v[14:15], v[4:5]
	v_lshlrev_b32_e32 v20, 16, v6
	v_pk_fma_f32 v[18:19], v[8:9], v[14:15], v[4:5] op_sel_hi:[0,1,1] neg_lo:[0,0,1] neg_hi:[0,0,1]
	v_pk_add_f32 v[4:5], v[30:31], v[52:53] neg_lo:[0,1] neg_hi:[0,1]
	v_and_b32_e32 v21, 0xffff0000, v6
	v_pk_add_f32 v[22:23], v[4:5], v[20:21]
	v_pk_add_f32 v[4:5], v[32:33], v[56:57] neg_lo:[0,1] neg_hi:[0,1]
	v_lshlrev_b32_e32 v6, 16, v7
	v_and_b32_e32 v7, 0xffff0000, v7
	v_pk_add_f32 v[26:27], v[4:5], v[6:7]
	v_min_i32_e32 v4, 7, v60
	v_add_u32_e32 v4, 1, v4
	v_cvt_f32_i32_e32 v28, v4
	v_pk_add_f32 v[10:11], v[10:11], v[12:13]
	v_pk_fma_f32 v[20:21], v[8:9], v[22:23], v[20:21] op_sel_hi:[0,1,1] neg_lo:[0,0,1] neg_hi:[0,0,1]
	v_pk_fma_f32 v[12:13], v[8:9], v[10:11], v[12:13] op_sel_hi:[0,1,1] neg_lo:[0,0,1] neg_hi:[0,0,1]
	v_cvt_pk_bf16_f32 v4, v12, v13
	v_div_scale_f32 v12, s[8:9], v28, v28, 1.0
	v_rcp_f32_e32 v13, v12
	v_pk_fma_f32 v[8:9], v[8:9], v[26:27], v[6:7] op_sel_hi:[0,1,1] neg_lo:[0,0,1] neg_hi:[0,0,1]
	v_cvt_pk_bf16_f32 v5, v18, v19
	v_cvt_pk_bf16_f32 v6, v20, v21
	v_cvt_pk_bf16_f32 v7, v8, v9
	global_store_dwordx4 v[24:25], v[4:7], off offset:1024
	v_lshlrev_b32_e32 v8, 16, v0
	v_and_b32_e32 v9, 0xffff0000, v0
	v_fma_f32 v4, -v12, v13, 1.0
	v_fmac_f32_e32 v13, v4, v13
	v_div_scale_f32 v4, vcc, 1.0, v28, 1.0
	v_mul_f32_e32 v5, v4, v13
	v_fma_f32 v6, -v12, v5, v4
	v_fmac_f32_e32 v5, v6, v13
	v_fma_f32 v4, -v12, v5, v4
	v_div_fmas_f32 v4, v4, v13, v5
	v_pk_add_f32 v[6:7], v[10:11], v[40:41] neg_lo:[0,1] neg_hi:[0,1]
	v_div_fixup_f32 v4, v4, v28, 1.0
	v_pk_add_f32 v[6:7], v[6:7], v[8:9]
	v_lshlrev_b32_e32 v0, 16, v1
	v_pk_fma_f32 v[6:7], v[4:5], v[6:7], v[8:9] op_sel_hi:[0,1,1] neg_lo:[0,0,1] neg_hi:[0,0,1]
	v_pk_add_f32 v[8:9], v[14:15], v[42:43] neg_lo:[0,1] neg_hi:[0,1]
	v_and_b32_e32 v1, 0xffff0000, v1
	v_pk_add_f32 v[8:9], v[8:9], v[0:1]
	v_lshlrev_b32_e32 v10, 16, v2
	v_pk_fma_f32 v[8:9], v[4:5], v[8:9], v[0:1] op_sel_hi:[0,1,1] neg_lo:[0,0,1] neg_hi:[0,0,1]
	v_pk_add_f32 v[0:1], v[22:23], v[36:37] neg_lo:[0,1] neg_hi:[0,1]
	v_and_b32_e32 v11, 0xffff0000, v2
	v_pk_add_f32 v[0:1], v[0:1], v[10:11]
	v_lshlrev_b32_e32 v2, 16, v3
	v_pk_fma_f32 v[10:11], v[4:5], v[0:1], v[10:11] op_sel_hi:[0,1,1] neg_lo:[0,0,1] neg_hi:[0,0,1]
	v_pk_add_f32 v[0:1], v[26:27], v[48:49] neg_lo:[0,1] neg_hi:[0,1]
	v_and_b32_e32 v3, 0xffff0000, v3
	v_pk_add_f32 v[0:1], v[0:1], v[2:3]
	s_nop 0
	v_pk_fma_f32 v[4:5], v[4:5], v[0:1], v[2:3] op_sel_hi:[0,1,1] neg_lo:[0,0,1] neg_hi:[0,0,1]
	v_cvt_pk_bf16_f32 v0, v6, v7
	v_cvt_pk_bf16_f32 v1, v8, v9
	v_cvt_pk_bf16_f32 v2, v10, v11
	v_cvt_pk_bf16_f32 v3, v4, v5
	global_store_dwordx4 v[16:17], v[0:3], off offset:1024
	s_cbranch_execnz .LBB0_386
	s_branch .LBB0_400
